# lever 4: static priority of the second wave group in the GEMM K-loops raised from 1 to 3
# baseline (speedup 1.0000x reference)
; #define PG8_STAGE(bufoff, gbase, voff) do { _Pragma("unroll") for (int _i = 0; _i < 2; ++_i) \
;     __builtin_amdgcn_global_load_lds((const unsigned*)((const char*)(gbase) + (voff)[_i]), (PG8_LAS unsigned*)(lds + (bufoff) + ldsw + _i * 8192), 16, 0, 0); } while (0)
; #define PG8_WAIT_V(n) asm volatile("s_waitcnt vmcnt(" #n ")" ::: "memory")
; #define PG8_BAR __builtin_amdgcn_s_barrier()
; template <class Epi>
; DI void gemm_phase(PG8_LAS unsigned char* lds, const Gemm g, const StaticOrder& S, const Epi& E) {
;     ...
;   for (int i = 0; i < 2; ++i) { int R, C; stage_rc(tid * 16 + i * 8192, R, C); const int Rb = Epi::PERM ? ((R & ~31) + perm32(R & 31)) : R;
;     voffA[i] = (unsigned)(R * g.lda + C) * 2u; voffB[i] = (unsigned)(Rb * K + C) * 2u; }
;   const size_t kstep = (size_t)(BK * 2);
;   const size_t hstepA = (size_t)HALF * g.lda * 2, hstepB = (size_t)HALF * K * 2;
;   const size_t tstepA = 2 * hstepA, tstepB = 2 * hstepB;
;   const unsigned ldsw = (unsigned)wid * 1024u;
;   const int aoff = lds_byte(wr * 64 + fr, fq * 8), boff = lds_byte(wc * 32 + fr, fq * 8);
;     ...
;   Unit cur, nxt; int ui = 0;
;   if (!S.next(0, cur)) return;
;   f32x4 acc[2][2][4][2];
; #pragma unroll
;   for (int a = 0; a < 2; ++a)
; #pragma unroll
;     for (int b = 0; b < 2; ++b)
; #pragma unroll
;       for (int m = 0; m < 4; ++m)
; #pragma unroll
;         for (int n = 0; n < 2; ++n) acc[a][b][m][n] = (f32x4){0.f, 0.f, 0.f, 0.f};
;   bf16x8 At[4][2], B0[2][2], B1[2][2];
;   const char* cA = (const char*)g.A + (size_t)cur.pm * tstepA; const char* cB = (const char*)g.Bt + (size_t)cur.pn * tstepB;
;   PG8_STAGE(PG8_SB(0, 0), cB, voffB); PG8_STAGE(PG8_SA(0, 0), cA, voffA); PG8_STAGE(PG8_SB(0, 1), cB + hstepB, voffB); PG8_STAGE(PG8_SA(0, 1), cA + hstepA, voffA);
;   if (wr == 1) PG8_BAR;
;   PG8_WAIT_V(4); PG8_BAR;
;   PG8_STAGE(PG8_SB(1, 0), cB + kstep, voffB); PG8_STAGE(PG8_SA(1, 0), cA + kstep, voffA); PG8_STAGE(PG8_SB(1, 1), cB + hstepB + kstep, voffB);
;   PG8_WAIT_V(6); PG8_BAR;
.LBB0_45:
	s_or_b64 exec, exec, s[30:31]
	v_readlane_b32 s30, v252, 6
	v_mov_b32_e32 v4, v200
	v_readlane_b32 s31, v252, 7
	s_waitcnt lgkmcnt(0)
	s_barrier
	s_andn2_b64 vcc, exec, s[30:31]
	v_readfirstlane_b32 s28, v4
	s_cbranch_vccnz .LBB0_57
	v_lshlrev_b32_e32 v0, 4, v4
	v_add_u32_e32 v3, 0x2000, v0
	v_ashrrev_i32_e32 v2, 31, v3
	v_lshrrev_b32_e32 v2, 22, v2
	v_add_u32_e32 v2, v3, v2
	v_ashrrev_i32_e32 v2, 10, v2
	v_lshlrev_b32_e32 v5, 5, v2
	v_and_b32_e32 v6, 32, v5
	v_mul_i32_i24_e32 v5, 0x400, v2
	v_sub_u32_e32 v3, v3, v5
	v_lshrrev_b32_e32 v5, 4, v3
	v_bitop3_b32 v5, v5, v3, 32 bitop3:0x6c
	v_ashrrev_i32_e32 v3, 31, v5
	v_lshrrev_b32_e32 v3, 26, v3
	v_add_u32_e32 v7, v5, v3
	v_ashrrev_i32_e32 v3, 6, v7
	v_and_b32_e32 v7, 0xc0, v7
	v_sub_u32_e32 v5, v5, v7
	v_ashrrev_i16_sdwa v5, v202, sext(v5) dst_sel:DWORD dst_unused:UNUSED_PAD src0_sel:DWORD src1_sel:BYTE_0
	v_lshlrev_b32_e32 v7, 3, v2
	v_bfe_i32 v5, v5, 0, 16
	v_and_b32_e32 v7, 0x1ffff0, v7
	v_add_u32_e32 v6, v6, v5
	v_add_lshl_u32 v7, v3, v7, 11
	v_lshl_add_u32 v130, v6, 1, v7
	v_ashrrev_i32_e32 v6, 31, v4
	v_lshrrev_b32_e32 v6, 26, v6
	v_add_u32_e32 v6, v4, v6
	v_ashrrev_i32_e32 v6, 6, v6
	v_lshlrev_b32_e32 v7, 5, v6
	v_and_b32_e32 v9, 32, v7
	v_bfe_i32 v7, v4, 27, 1
	v_lshrrev_b32_e32 v7, 22, v7
	v_add_u32_e32 v7, v0, v7
	v_and_b32_e32 v7, 0xfffffc00, v7
	v_sub_u32_e32 v0, v0, v7
	v_lshrrev_b32_e32 v7, 4, v0
	v_bitop3_b32 v8, v7, v0, 32 bitop3:0x6c
	v_ashrrev_i32_e32 v0, 31, v0
	v_lshrrev_b32_e32 v0, 26, v0
	v_add_u32_e32 v0, v8, v0
	v_ashrrev_i32_e32 v7, 6, v0
	v_mul_i32_i24_e32 v0, 64, v7
	v_sub_u32_e32 v0, v8, v0
	v_ashrrev_i16_sdwa v0, v202, sext(v0) dst_sel:DWORD dst_unused:UNUSED_PAD src0_sel:DWORD src1_sel:BYTE_0
	v_bfe_i32 v8, v0, 0, 16
	s_ashr_i32 s30, s28, 6
	v_add_u32_e32 v0, v9, v8
	v_lshlrev_b32_e32 v9, 3, v6
	s_lshl_b32 s34, s30, 10
	v_and_b32_e32 v9, 0x1ffff0, v9
	v_add_lshl_u32 v9, v7, v9, 11
	s_add_i32 s37, s34, 0
	v_readlane_b32 s40, v252, 19
	v_lshl_add_u32 v0, v0, 1, v9
	s_add_i32 m0, s37, 0x10000
	v_readlane_b32 s41, v252, 20
	s_add_i32 s62, s37, 0x2000
	s_add_i32 s63, s37, 0x4000
	s_add_i32 s64, s37, 0x6000
	s_ashr_i32 s31, s28, 8
	s_nop 0
	global_load_lds_dwordx4 v0, s[40:41]
	s_add_i32 m0, s37, 0x12000
	s_nop 0
	global_load_lds_dwordx4 v130, s[40:41]
	v_readlane_b32 s40, v252, 15
	s_mov_b32 m0, s37
	v_readlane_b32 s41, v252, 16
	s_nop 4
	global_load_lds_dwordx4 v0, s[40:41]
	s_mov_b32 m0, s62
	s_nop 0
	global_load_lds_dwordx4 v130, s[40:41]
	v_readlane_b32 s40, v252, 13
	s_add_i32 m0, s37, 0x14000
	v_readlane_b32 s41, v252, 14
	s_nop 4
	global_load_lds_dwordx4 v0, s[40:41]
	s_add_i32 m0, s37, 0x16000
	s_cmp_lg_u32 s31, 1
	global_load_lds_dwordx4 v130, s[40:41]
	v_readlane_b32 s40, v252, 17
	s_mov_b32 m0, s63
	v_readlane_b32 s41, v252, 18
	s_nop 4
	global_load_lds_dwordx4 v0, s[40:41]
	s_mov_b32 m0, s64
	s_nop 0
	global_load_lds_dwordx4 v130, s[40:41]
	s_cbranch_scc1 .LBB0_48
	s_barrier
	s_setprio 3

; #define PG8_STAGE(bufoff, gbase, voff) do { _Pragma("unroll") for (int _i = 0; _i < 2; ++_i) \
;     __builtin_amdgcn_global_load_lds((const unsigned*)((const char*)(gbase) + (voff)[_i]), (PG8_LAS unsigned*)(lds + (bufoff) + ldsw + _i * 8192), 16, 0, 0); } while (0)
; #define PG8_WAIT_V(n) asm volatile("s_waitcnt vmcnt(" #n ")" ::: "memory")
; #define PG8_BAR __builtin_amdgcn_s_barrier()
; template <class Epi>
; DI void gemm_phase(PG8_LAS unsigned char* lds, const Gemm g, const StaticOrder& S, const Epi& E) {
;     ...
;   for (int i = 0; i < 2; ++i) { int R, C; stage_rc(tid * 16 + i * 8192, R, C); const int Rb = Epi::PERM ? ((R & ~31) + perm32(R & 31)) : R;
;     voffA[i] = (unsigned)(R * g.lda + C) * 2u; voffB[i] = (unsigned)(Rb * K + C) * 2u; }
;   const size_t kstep = (size_t)(BK * 2);
;   const size_t hstepA = (size_t)HALF * g.lda * 2, hstepB = (size_t)HALF * K * 2;
;   const size_t tstepA = 2 * hstepA, tstepB = 2 * hstepB;
;   const unsigned ldsw = (unsigned)wid * 1024u;
;   const int aoff = lds_byte(wr * 64 + fr, fq * 8), boff = lds_byte(wc * 32 + fr, fq * 8);
;     ...
;   Unit cur, nxt; int ui = 0;
;   if (!S.next(0, cur)) return;
;   f32x4 acc[2][2][4][2];
; #pragma unroll
;   for (int a = 0; a < 2; ++a)
; #pragma unroll
;     for (int b = 0; b < 2; ++b)
; #pragma unroll
;       for (int m = 0; m < 4; ++m)
; #pragma unroll
;         for (int n = 0; n < 2; ++n) acc[a][b][m][n] = (f32x4){0.f, 0.f, 0.f, 0.f};
;   bf16x8 At[4][2], B0[2][2], B1[2][2];
;   const char* cA = (const char*)g.A + (size_t)cur.pm * tstepA; const char* cB = (const char*)g.Bt + (size_t)cur.pn * tstepB;
;   PG8_STAGE(PG8_SB(0, 0), cB, voffB); PG8_STAGE(PG8_SA(0, 0), cA, voffA); PG8_STAGE(PG8_SB(0, 1), cB + hstepB, voffB); PG8_STAGE(PG8_SA(0, 1), cA + hstepA, voffA);
;   if (wr == 1) PG8_BAR;
;   PG8_WAIT_V(4); PG8_BAR;
;   PG8_STAGE(PG8_SB(1, 0), cB + kstep, voffB); PG8_STAGE(PG8_SA(1, 0), cA + kstep, voffA); PG8_STAGE(PG8_SB(1, 1), cB + hstepB + kstep, voffB);
;   PG8_WAIT_V(6); PG8_BAR;
.LBB0_819:
	v_readlane_b32 s4, v252, 37
	s_waitcnt vmcnt(7)
	v_mov_b32_e32 v14, v200
	v_readlane_b32 s5, v252, 38
	s_barrier
	s_andn2_b64 vcc, exec, s[4:5]
	v_readfirstlane_b32 s28, v14
	s_cbranch_vccnz .LBB0_991
	v_lshlrev_b32_e32 v0, 4, v14
	s_waitcnt vmcnt(0)
	v_add_u32_e32 v2, 0x2000, v0
	v_ashrrev_i32_e32 v3, 31, v2
	v_lshrrev_b32_e32 v3, 22, v3
	v_add_u32_e32 v3, v2, v3
	v_ashrrev_i32_e32 v3, 10, v3
	v_lshlrev_b32_e32 v4, 5, v3
	v_and_b32_e32 v15, 32, v4
	v_mul_i32_i24_e32 v4, 0x400, v3
	v_sub_u32_e32 v2, v2, v4
	v_lshrrev_b32_e32 v4, 4, v2
	v_bitop3_b32 v2, v4, v2, 32 bitop3:0x6c
	v_ashrrev_i32_e32 v4, 31, v2
	v_lshrrev_b32_e32 v4, 26, v4
	v_add_u32_e32 v4, v2, v4
	v_ashrrev_i32_e32 v5, 6, v4
	v_and_b32_e32 v4, 0xc0, v4
	v_sub_u32_e32 v2, v2, v4
	v_lshlrev_b32_e32 v3, 3, v3
	v_ashrrev_i16_sdwa v2, v202, sext(v2) dst_sel:DWORD dst_unused:UNUSED_PAD src0_sel:DWORD src1_sel:BYTE_0
	v_and_b32_e32 v3, -16, v3
	v_bfe_i32 v16, v2, 0, 16
	v_add_u32_e32 v3, v5, v3
	v_add_u32_e32 v2, v15, v16
	v_mul_lo_u32 v4, v3, s34
	v_mul_lo_u32 v17, v3, s40
	v_add_lshl_u32 v142, v2, v4, 1
	v_add_lshl_u32 v144, v2, v17, 1
	v_ashrrev_i32_e32 v2, 31, v14
	v_lshrrev_b32_e32 v2, 26, v2
	v_add_u32_e32 v2, v14, v2
	v_ashrrev_i32_e32 v2, 6, v2
	v_lshlrev_b32_e32 v3, 5, v2
	v_and_b32_e32 v18, 32, v3
	v_bfe_i32 v3, v14, 27, 1
	v_lshrrev_b32_e32 v3, 22, v3
	v_add_u32_e32 v3, v0, v3
	v_and_b32_e32 v3, 0xfffffc00, v3
	v_sub_u32_e32 v0, v0, v3
	v_lshrrev_b32_e32 v3, 4, v0
	v_readlane_b32 s4, v253, 16
	v_bitop3_b32 v3, v3, v0, 32 bitop3:0x6c
	v_ashrrev_i32_e32 v0, 31, v0
	v_readlane_b32 s14, v253, 26
	v_lshrrev_b32_e32 v0, 26, v0
	v_readlane_b32 s15, v253, 27
	s_add_u32 s37, s14, s0
	v_add_u32_e32 v0, v3, v0
	v_lshlrev_b32_e32 v2, 3, v2
	s_addc_u32 s60, s15, s1
	v_readlane_b32 s0, v252, 4
	v_ashrrev_i32_e32 v0, 6, v0
	v_and_b32_e32 v2, -16, v2
	v_readlane_b32 s5, v253, 17
	v_readlane_b32 s1, v252, 5
	s_lshl_b32 s63, s40, 9
	v_mul_i32_i24_e32 v4, 64, v0
	v_add_u32_e32 v2, v0, v2
	v_readlane_b32 s4, v255, 0
	s_load_dword s61, s[0:1], 0x0
	s_ashr_i32 s1, s28, 6
	s_lshl_b32 s50, s40, 8
	s_lshl_b32 s64, s34, 9
	v_sub_u32_e32 v3, v3, v4
	v_mul_lo_u32 v20, v2, s40
	s_mul_hi_i32 s40, s63, s4
	s_mul_i32 s41, s63, s4
	v_readlane_b32 s4, v255, 2
	s_ashr_i32 s0, s28, 8
	s_lshl_b32 s62, s34, 8
	s_lshl_b32 s65, s1, 10
	v_ashrrev_i16_sdwa v3, v202, sext(v3) dst_sel:DWORD dst_unused:UNUSED_PAD src0_sel:DWORD src1_sel:BYTE_0
	s_mul_i32 s43, s64, s4
	v_bfe_i32 v19, v3, 0, 16
	s_mul_hi_i32 s42, s64, s4
	s_add_u32 s56, s37, s43
	v_add_u32_e32 v3, v18, v19
	v_mul_lo_u32 v0, v2, s34
	s_addc_u32 s57, s60, s42
	s_add_i32 s66, s65, 0
	v_add_lshl_u32 v0, v3, v0, 1
	s_add_i32 m0, s66, 0x10000
	v_add_lshl_u32 v146, v3, v20, 1
	global_load_lds_dwordx4 v0, s[56:57]
	s_add_i32 m0, s66, 0x12000
	s_add_u32 s58, s30, s41
	global_load_lds_dwordx4 v142, s[56:57]
	s_addc_u32 s59, s31, s40
	s_mov_b32 m0, s66
	s_add_i32 s67, s66, 0x2000
	global_load_lds_dwordx4 v146, s[58:59]
	s_mov_b32 m0, s67
	s_add_u32 s40, s56, s62
	global_load_lds_dwordx4 v144, s[58:59]
	s_addc_u32 s41, s57, 0
	s_add_i32 m0, s66, 0x14000
	v_mov_b32_e32 v143, v1
	global_load_lds_dwordx4 v0, s[40:41]
	s_add_i32 m0, s66, 0x16000
	s_waitcnt lgkmcnt(0)
	v_lshl_add_u64 v[10:11], s[40:41], 0, v[0:1]
	v_lshl_add_u64 v[12:13], s[40:41], 0, v[142:143]
	global_load_lds_dwordx4 v142, s[40:41]
	s_add_u32 s40, s58, s50
	s_addc_u32 s41, s59, 0
	s_add_i32 s68, s66, 0x4000
	s_mov_b32 m0, s68
	s_add_i32 s69, s66, 0x6000
	global_load_lds_dwordx4 v146, s[40:41]
	s_mov_b32 m0, s69
	v_mov_b32_e32 v147, v1
	global_load_lds_dwordx4 v144, s[40:41]
	v_mov_b32_e32 v145, v1
	s_mov_b32 s51, s35
	v_lshl_add_u64 v[2:3], s[56:57], 0, v[0:1]
	v_lshl_add_u64 v[4:5], s[56:57], 0, v[142:143]
	v_lshl_add_u64 v[6:7], s[58:59], 0, v[146:147]
	v_lshl_add_u64 v[8:9], s[58:59], 0, v[144:145]
	s_cmp_lg_u32 s0, 1
	v_readlane_b32 s6, v253, 18
	v_readlane_b32 s7, v253, 19
	v_readlane_b32 s8, v253, 20
	v_readlane_b32 s9, v253, 21
	v_readlane_b32 s10, v253, 22
	v_readlane_b32 s11, v253, 23
	v_readlane_b32 s12, v253, 24
	v_readlane_b32 s13, v253, 25
	v_readlane_b32 s16, v253, 28
	v_readlane_b32 s17, v253, 29
	v_readlane_b32 s18, v253, 30
	v_readlane_b32 s19, v253, 31
	v_readlane_b32 s5, v255, 3
	s_cbranch_scc1 .LBB0_822
	s_barrier
	s_setprio 3

; #define PG8_STAGE(bufoff, gbase, voff) do { _Pragma("unroll") for (int _i = 0; _i < 2; ++_i) \
;     __builtin_amdgcn_global_load_lds((const unsigned*)((const char*)(gbase) + (voff)[_i]), (PG8_LAS unsigned*)(lds + (bufoff) + ldsw + _i * 8192), 16, 0, 0); } while (0)
; #define PG8_WAIT_V(n) asm volatile("s_waitcnt vmcnt(" #n ")" ::: "memory")
; #define PG8_BAR __builtin_amdgcn_s_barrier()
; template <class Epi>
; DI void gemm_phase(PG8_LAS unsigned char* lds, const Gemm g, const StaticOrder& S, const Epi& E) {
;     ...
;   for (int i = 0; i < 2; ++i) { int R, C; stage_rc(tid * 16 + i * 8192, R, C); const int Rb = Epi::PERM ? ((R & ~31) + perm32(R & 31)) : R;
;     voffA[i] = (unsigned)(R * g.lda + C) * 2u; voffB[i] = (unsigned)(Rb * K + C) * 2u; }
;   const size_t kstep = (size_t)(BK * 2);
;   const size_t hstepA = (size_t)HALF * g.lda * 2, hstepB = (size_t)HALF * K * 2;
;   const size_t tstepA = 2 * hstepA, tstepB = 2 * hstepB;
;   const unsigned ldsw = (unsigned)wid * 1024u;
;   const int aoff = lds_byte(wr * 64 + fr, fq * 8), boff = lds_byte(wc * 32 + fr, fq * 8);
;     ...
;   Unit cur, nxt; int ui = 0;
;   if (!S.next(0, cur)) return;
;   f32x4 acc[2][2][4][2];
; #pragma unroll
;   for (int a = 0; a < 2; ++a)
; #pragma unroll
;     for (int b = 0; b < 2; ++b)
; #pragma unroll
;       for (int m = 0; m < 4; ++m)
; #pragma unroll
;         for (int n = 0; n < 2; ++n) acc[a][b][m][n] = (f32x4){0.f, 0.f, 0.f, 0.f};
;   bf16x8 At[4][2], B0[2][2], B1[2][2];
;   const char* cA = (const char*)g.A + (size_t)cur.pm * tstepA; const char* cB = (const char*)g.Bt + (size_t)cur.pn * tstepB;
;   PG8_STAGE(PG8_SB(0, 0), cB, voffB); PG8_STAGE(PG8_SA(0, 0), cA, voffA); PG8_STAGE(PG8_SB(0, 1), cB + hstepB, voffB); PG8_STAGE(PG8_SA(0, 1), cA + hstepA, voffA);
;   if (wr == 1) PG8_BAR;
;   PG8_WAIT_V(4); PG8_BAR;
;   PG8_STAGE(PG8_SB(1, 0), cB + kstep, voffB); PG8_STAGE(PG8_SA(1, 0), cA + kstep, voffA); PG8_STAGE(PG8_SB(1, 1), cB + hstepB + kstep, voffB);
;   PG8_WAIT_V(6); PG8_BAR;
.LBB0_1167:
	s_or_b64 exec, exec, s[30:31]
	v_readlane_b32 s4, v252, 48
	v_mov_b32_e32 v4, v200
	v_readlane_b32 s5, v252, 49
	s_waitcnt lgkmcnt(0)
	s_barrier
	s_andn2_b64 vcc, exec, s[4:5]
	v_readfirstlane_b32 s56, v4
	s_cbranch_vccnz .LBB0_1184
	v_lshlrev_b32_e32 v0, 4, v4
	v_add_u32_e32 v3, 0x2000, v0
	v_ashrrev_i32_e32 v2, 31, v3
	v_lshrrev_b32_e32 v2, 22, v2
	v_add_u32_e32 v2, v3, v2
	v_ashrrev_i32_e32 v2, 10, v2
	v_mul_i32_i24_e32 v5, 0x400, v2
	v_sub_u32_e32 v3, v3, v5
	v_lshrrev_b32_e32 v5, 4, v3
	v_bitop3_b32 v5, v5, v3, 32 bitop3:0x6c
	v_ashrrev_i32_e32 v3, 31, v5
	v_lshrrev_b32_e32 v3, 26, v3
	v_add_u32_e32 v6, v5, v3
	v_lshlrev_b32_e32 v7, 3, v2
	v_ashrrev_i32_e32 v3, 6, v6
	v_and_b32_e32 v7, -16, v7
	v_add_u32_e32 v7, v3, v7
	v_and_b32_e32 v8, 3, v3
	s_mov_b32 s4, 0x1fffe0
	v_lshrrev_b32_e32 v9, 2, v7
	v_lshlrev_b32_e32 v10, 1, v7
	v_and_b32_e32 v6, 0xc0, v6
	v_and_or_b32 v8, v7, s4, v8
	v_and_b32_e32 v9, 4, v9
	v_and_b32_e32 v10, 24, v10
	v_sub_u32_e32 v5, v5, v6
	v_or3_b32 v8, v8, v9, v10
	v_lshlrev_b32_e32 v9, 5, v2
	v_ashrrev_i16_sdwa v5, v202, sext(v5) dst_sel:DWORD dst_unused:UNUSED_PAD src0_sel:DWORD src1_sel:BYTE_0
	v_and_b32_e32 v9, 32, v9
	v_bfe_i32 v5, v5, 0, 16
	v_add_lshl_u32 v6, v9, v5, 1
	v_lshl_add_u32 v130, v8, 11, v6
	v_lshl_add_u32 v132, v7, 11, v6
	v_bfe_i32 v6, v4, 27, 1
	v_lshrrev_b32_e32 v6, 22, v6
	v_add_u32_e32 v6, v0, v6
	v_and_b32_e32 v6, 0xfffffc00, v6
	v_sub_u32_e32 v0, v0, v6
	v_lshrrev_b32_e32 v6, 4, v0
	v_bitop3_b32 v8, v6, v0, 32 bitop3:0x6c
	v_ashrrev_i32_e32 v0, 31, v0
	v_lshrrev_b32_e32 v0, 26, v0
	v_add_u32_e32 v0, v8, v0
	v_ashrrev_i32_e32 v6, 6, v0
	v_ashrrev_i32_e32 v0, 31, v4
	v_lshrrev_b32_e32 v0, 26, v0
	v_add_u32_e32 v0, v4, v0
	v_ashrrev_i32_e32 v7, 6, v0
	v_lshlrev_b32_e32 v0, 3, v7
	v_and_b32_e32 v0, -16, v0
	v_add_u32_e32 v9, v6, v0
	v_and_b32_e32 v0, 3, v6
	v_lshrrev_b32_e32 v10, 2, v9
	v_lshlrev_b32_e32 v11, 1, v9
	v_and_or_b32 v0, v9, s4, v0
	v_and_b32_e32 v10, 4, v10
	v_and_b32_e32 v11, 24, v11
	v_or3_b32 v0, v0, v10, v11
	v_mul_i32_i24_e32 v11, 64, v6
	v_sub_u32_e32 v8, v8, v11
	s_ashr_i32 s28, s56, 6
	v_lshlrev_b32_e32 v10, 5, v7
	v_ashrrev_i16_sdwa v8, v202, sext(v8) dst_sel:DWORD dst_unused:UNUSED_PAD src0_sel:DWORD src1_sel:BYTE_0
	s_lshl_b32 s57, s28, 10
	v_and_b32_e32 v10, 32, v10
	v_bfe_i32 v8, v8, 0, 16
	v_add_lshl_u32 v10, v10, v8, 1
	s_add_i32 s58, s57, 0
	v_readlane_b32 s4, v252, 59
	v_lshl_add_u32 v0, v0, 11, v10
	s_add_i32 m0, s58, 0x10000
	v_readlane_b32 s5, v252, 60
	v_lshl_add_u32 v142, v9, 11, v10
	s_add_i32 s59, s58, 0x2000
	s_add_i32 s60, s58, 0x4000
	s_add_i32 s61, s58, 0x6000
	s_ashr_i32 s30, s56, 8
	global_load_lds_dwordx4 v0, s[4:5]
	s_add_i32 m0, s58, 0x12000
	s_nop 0
	global_load_lds_dwordx4 v130, s[4:5]
	v_readlane_b32 s4, v252, 55
	s_mov_b32 m0, s58
	v_readlane_b32 s5, v252, 56
	s_nop 4
	global_load_lds_dwordx4 v142, s[4:5]
	s_mov_b32 m0, s59
	s_nop 0
	global_load_lds_dwordx4 v132, s[4:5]
	v_readlane_b32 s4, v252, 53
	s_add_i32 m0, s58, 0x14000
	v_readlane_b32 s5, v252, 54
	s_nop 4
	global_load_lds_dwordx4 v0, s[4:5]
	s_add_i32 m0, s58, 0x16000
	s_cmp_lg_u32 s30, 1
	global_load_lds_dwordx4 v130, s[4:5]
	v_readlane_b32 s4, v252, 57
	s_mov_b32 m0, s60
	v_readlane_b32 s5, v252, 58
	s_nop 4
	global_load_lds_dwordx4 v142, s[4:5]
	s_mov_b32 m0, s61
	s_nop 0
	global_load_lds_dwordx4 v132, s[4:5]
	s_cbranch_scc1 .LBB0_1170
	s_barrier
	s_setprio 3

; #define PG8_STAGE(bufoff, gbase, voff) do { _Pragma("unroll") for (int _i = 0; _i < 2; ++_i) \
;     __builtin_amdgcn_global_load_lds((const unsigned*)((const char*)(gbase) + (voff)[_i]), (PG8_LAS unsigned*)(lds + (bufoff) + ldsw + _i * 8192), 16, 0, 0); } while (0)
; #define PG8_WAIT_V(n) asm volatile("s_waitcnt vmcnt(" #n ")" ::: "memory")
; #define PG8_BAR __builtin_amdgcn_s_barrier()
; template <class Epi>
; DI void gemm_phase(PG8_LAS unsigned char* lds, const Gemm g, const StaticOrder& S, const Epi& E) {
;     ...
;   for (int i = 0; i < 2; ++i) { int R, C; stage_rc(tid * 16 + i * 8192, R, C); const int Rb = Epi::PERM ? ((R & ~31) + perm32(R & 31)) : R;
;     voffA[i] = (unsigned)(R * g.lda + C) * 2u; voffB[i] = (unsigned)(Rb * K + C) * 2u; }
;   const size_t kstep = (size_t)(BK * 2);
;   const size_t hstepA = (size_t)HALF * g.lda * 2, hstepB = (size_t)HALF * K * 2;
;   const size_t tstepA = 2 * hstepA, tstepB = 2 * hstepB;
;   const unsigned ldsw = (unsigned)wid * 1024u;
;   const int aoff = lds_byte(wr * 64 + fr, fq * 8), boff = lds_byte(wc * 32 + fr, fq * 8);
;     ...
;   Unit cur, nxt; int ui = 0;
;   if (!S.next(0, cur)) return;
;   f32x4 acc[2][2][4][2];
; #pragma unroll
;   for (int a = 0; a < 2; ++a)
; #pragma unroll
;     for (int b = 0; b < 2; ++b)
; #pragma unroll
;       for (int m = 0; m < 4; ++m)
; #pragma unroll
;         for (int n = 0; n < 2; ++n) acc[a][b][m][n] = (f32x4){0.f, 0.f, 0.f, 0.f};
;   bf16x8 At[4][2], B0[2][2], B1[2][2];
;   const char* cA = (const char*)g.A + (size_t)cur.pm * tstepA; const char* cB = (const char*)g.Bt + (size_t)cur.pn * tstepB;
;   PG8_STAGE(PG8_SB(0, 0), cB, voffB); PG8_STAGE(PG8_SA(0, 0), cA, voffA); PG8_STAGE(PG8_SB(0, 1), cB + hstepB, voffB); PG8_STAGE(PG8_SA(0, 1), cA + hstepA, voffA);
;   if (wr == 1) PG8_BAR;
;   PG8_WAIT_V(4); PG8_BAR;
;   PG8_STAGE(PG8_SB(1, 0), cB + kstep, voffB); PG8_STAGE(PG8_SA(1, 0), cA + kstep, voffA); PG8_STAGE(PG8_SB(1, 1), cB + hstepB + kstep, voffB);
;   PG8_WAIT_V(6); PG8_BAR;
.LBB0_1190:
	s_or_b64 exec, exec, s[30:31]
	v_readlane_b32 s4, v253, 1
	v_mov_b32_e32 v4, v200
	v_readlane_b32 s5, v253, 2
	s_waitcnt lgkmcnt(0)
	s_barrier
	s_andn2_b64 vcc, exec, s[4:5]
	v_readfirstlane_b32 s28, v4
	s_cbranch_vccnz .LBB0_1202
	v_lshlrev_b32_e32 v0, 4, v4
	v_add_u32_e32 v3, 0x2000, v0
	v_ashrrev_i32_e32 v2, 31, v3
	v_lshrrev_b32_e32 v2, 22, v2
	v_add_u32_e32 v2, v3, v2
	v_ashrrev_i32_e32 v2, 10, v2
	v_mul_i32_i24_e32 v5, 0x400, v2
	v_sub_u32_e32 v3, v3, v5
	v_lshrrev_b32_e32 v5, 4, v3
	v_bitop3_b32 v5, v5, v3, 32 bitop3:0x6c
	v_ashrrev_i32_e32 v3, 31, v5
	v_lshrrev_b32_e32 v3, 26, v3
	v_add_u32_e32 v6, v5, v3
	v_lshlrev_b32_e32 v7, 3, v2
	v_ashrrev_i32_e32 v3, 6, v6
	v_and_b32_e32 v7, -16, v7
	v_add_u32_e32 v7, v3, v7
	v_and_b32_e32 v8, 3, v3
	s_mov_b32 s4, 0x1fffe0
	v_lshrrev_b32_e32 v9, 2, v7
	v_lshlrev_b32_e32 v10, 1, v7
	v_and_b32_e32 v6, 0xc0, v6
	v_and_or_b32 v8, v7, s4, v8
	v_and_b32_e32 v9, 4, v9
	v_and_b32_e32 v10, 24, v10
	v_sub_u32_e32 v5, v5, v6
	v_or3_b32 v8, v8, v9, v10
	v_lshlrev_b32_e32 v9, 5, v2
	v_ashrrev_i16_sdwa v5, v202, sext(v5) dst_sel:DWORD dst_unused:UNUSED_PAD src0_sel:DWORD src1_sel:BYTE_0
	v_and_b32_e32 v9, 32, v9
	v_bfe_i32 v5, v5, 0, 16
	v_add_lshl_u32 v6, v9, v5, 1
	v_lshl_add_u32 v130, v8, 11, v6
	v_lshl_add_u32 v132, v7, 11, v6
	v_bfe_i32 v6, v4, 27, 1
	v_lshrrev_b32_e32 v6, 22, v6
	v_add_u32_e32 v6, v0, v6
	v_and_b32_e32 v6, 0xfffffc00, v6
	v_sub_u32_e32 v0, v0, v6
	v_lshrrev_b32_e32 v6, 4, v0
	v_bitop3_b32 v8, v6, v0, 32 bitop3:0x6c
	v_ashrrev_i32_e32 v0, 31, v0
	v_lshrrev_b32_e32 v0, 26, v0
	v_add_u32_e32 v0, v8, v0
	v_ashrrev_i32_e32 v6, 6, v0
	v_ashrrev_i32_e32 v0, 31, v4
	v_lshrrev_b32_e32 v0, 26, v0
	v_add_u32_e32 v0, v4, v0
	v_ashrrev_i32_e32 v7, 6, v0
	v_lshlrev_b32_e32 v0, 3, v7
	v_and_b32_e32 v0, -16, v0
	v_add_u32_e32 v9, v6, v0
	v_and_b32_e32 v0, 3, v6
	v_lshrrev_b32_e32 v10, 2, v9
	v_lshlrev_b32_e32 v11, 1, v9
	v_and_or_b32 v0, v9, s4, v0
	v_and_b32_e32 v10, 4, v10
	v_and_b32_e32 v11, 24, v11
	v_or3_b32 v0, v0, v10, v11
	v_mul_i32_i24_e32 v11, 64, v6
	v_sub_u32_e32 v8, v8, v11
	s_ashr_i32 s30, s28, 6
	v_lshlrev_b32_e32 v10, 5, v7
	v_ashrrev_i16_sdwa v8, v202, sext(v8) dst_sel:DWORD dst_unused:UNUSED_PAD src0_sel:DWORD src1_sel:BYTE_0
	s_lshl_b32 s34, s30, 10
	v_and_b32_e32 v10, 32, v10
	v_bfe_i32 v8, v8, 0, 16
	v_add_lshl_u32 v10, v10, v8, 1
	s_add_i32 s37, s34, 0
	v_readlane_b32 s4, v253, 12
	v_lshl_add_u32 v0, v0, 11, v10
	s_add_i32 m0, s37, 0x10000
	v_readlane_b32 s5, v253, 13
	v_lshl_add_u32 v142, v9, 11, v10
	s_add_i32 s54, s37, 0x2000
	s_add_i32 s55, s37, 0x4000
	s_add_i32 s56, s37, 0x6000
	s_ashr_i32 s31, s28, 8
	global_load_lds_dwordx4 v0, s[4:5]
	s_add_i32 m0, s37, 0x12000
	s_nop 0
	global_load_lds_dwordx4 v130, s[4:5]
	v_readlane_b32 s4, v253, 8
	s_mov_b32 m0, s37
	v_readlane_b32 s5, v253, 9
	s_nop 4
	global_load_lds_dwordx4 v142, s[4:5]
	s_mov_b32 m0, s54
	s_nop 0
	global_load_lds_dwordx4 v132, s[4:5]
	v_readlane_b32 s4, v253, 6
	s_add_i32 m0, s37, 0x14000
	v_readlane_b32 s5, v253, 7
	s_nop 4
	global_load_lds_dwordx4 v0, s[4:5]
	s_add_i32 m0, s37, 0x16000
	s_cmp_lg_u32 s31, 1
	global_load_lds_dwordx4 v130, s[4:5]
	v_readlane_b32 s4, v253, 10
	s_mov_b32 m0, s55
	v_readlane_b32 s5, v253, 11
	s_nop 4
	global_load_lds_dwordx4 v142, s[4:5]
	s_mov_b32 m0, s56
	s_nop 0
	global_load_lds_dwordx4 v132, s[4:5]
	s_cbranch_scc1 .LBB0_1193
	s_barrier
	s_setprio 3
